# out-projection epilogue: residual rows of row-groups 1-3 touched (dword per line) alongside group 0's loads so the later serialized groups hit L2; on comb15
# baseline (speedup 1.0000x reference)
;     __device__ __forceinline__ void operator()(const pg8::f32x4 (&acc)[2][2][4][2], const pg8::Unit& u, int wr, int wc, int fr, int fq) const {
;     ...
;         const float* const xp = q->in[I_XP];
;         const float* const MOD = (const float*)(q->ws + WS_MOD); bf16* const X = (bf16*)(q->ws + WS_X);
;         const int cb = u.pn * 256 + wc * 32 + 8 * fq;
;         f32x4 gv[4];
;         { const float* gate = MOD + (size_t)(l * 12 + modrow(u.pm * 256)) * 12288 + 8192 + cb;
;           gv[0] = *(const f32x4*)gate; gv[1] = *(const f32x4*)(gate + 4); gv[2] = *(const f32x4*)(gate + 128); gv[3] = *(const f32x4*)(gate + 132); }
; #pragma unroll
;         for (int ai = 0; ai < 2; ++ai)
; #pragma unroll
;             for (int mp = 0; mp < 2; ++mp) {
;                 f32x4 xv[2][4];
; #pragma unroll
;                 for (int k = 0; k < 2; ++k) {
;                     const int m = mp * 2 + k;
;                     const int r = u.pm * 256 + ai * 128 + wr * 64 + m * 16 + fr;
; #pragma unroll
;                     for (int bj = 0; bj < 2; ++bj) {
;                         const int cc = cb + bj * 128;
;                         if (l == 0) { const float* xo = xp + (size_t)r * DM + cc; xv[k][bj * 2] = *(const f32x4*)xo; xv[k][bj * 2 + 1] = *(const f32x4*)(xo + 4); }
;                         else { const u32x4 w = *(const u32x4*)(X + (size_t)r * DM + cc);
;                             xv[k][bj * 2] = (f32x4){__uint_as_float(w.x << 16), __uint_as_float(w.x & 0xFFFF0000u), __uint_as_float(w.y << 16), __uint_as_float(w.y & 0xFFFF0000u)};
;                             xv[k][bj * 2 + 1] = (f32x4){__uint_as_float(w.z << 16), __uint_as_float(w.z & 0xFFFF0000u), __uint_as_float(w.w << 16), __uint_as_float(w.w & 0xFFFF0000u)}; }
;                     }
;                 }
; #pragma unroll
;                 for (int k = 0; k < 2; ++k) {
;                     const int m = mp * 2 + k;
;                     const int r = u.pm * 256 + ai * 128 + wr * 64 + m * 16 + fr;
; #pragma unroll
;                     for (int bj = 0; bj < 2; ++bj) {
;                         const f32x4 o0 = xv[k][bj * 2] + gv[bj * 2] * acc[ai][bj][m][0], o1 = xv[k][bj * 2 + 1] + gv[bj * 2 + 1] * acc[ai][bj][m][1];
;                         *(u32x4*)(X + (size_t)r * DM + cb + bj * 128) = (u32x4){pk2(o0[0], o0[1]), pk2(o0[2], o0[3]), pk2(o1[0], o1[1]), pk2(o1[2], o1[3])};
;                     }
.LBB0_1616:
	s_mov_b64 s[28:29], s[90:91]
	s_lshl_b32 s17, s24, 8
	s_add_i32 s30, s17, 0xffffe000
	s_load_dwordx2 s[26:27], s[28:29], 0x0
	s_nop 0
	s_load_dwordx2 s[28:29], s[28:29], 0xc0
	s_lshr_b32 s30, s30, 2
	s_ashr_i32 s19, s24, 3
	s_or_b32 s30, s30, 4
	s_cmp_lt_i32 s24, 32
	s_cselect_b32 s19, s19, s30
	v_lshl_or_b32 v164, s50, 8, v170
	s_mul_hi_i32 s24, s19, 0xc000
	s_mul_i32 s19, s19, 0xc000
	v_add_u32_e32 v162, s17, v168
	s_waitcnt lgkmcnt(0)
	s_add_u32 s30, s28, s19
	v_ashrrev_i32_e32 v165, 31, v164
	v_or_b32_e32 v206, 16, v162
	s_addc_u32 s31, s29, s24
	v_lshlrev_b64 v[160:161], 2, v[164:165]
	v_ashrrev_i32_e32 v163, 31, v162
	v_ashrrev_i32_e32 v207, 31, v206
	v_lshl_add_u64 v[128:129], s[30:31], 0, v[160:161]
	v_lshlrev_b64 v[174:175], 14, v[162:163]
	v_lshlrev_b64 v[190:191], 14, v[206:207]
	v_lshl_add_u64 v[136:137], v[128:129], 0, s[12:13]
	v_add_co_u32_e32 v128, vcc, s49, v128
	v_lshl_add_u64 v[174:175], s[26:27], 0, v[174:175]
	v_lshl_add_u64 v[190:191], s[26:27], 0, v[190:191]
	v_addc_co_u32_e32 v129, vcc, 0, v129, vcc
	v_lshl_add_u64 v[186:187], v[174:175], 0, v[160:161]
	v_lshl_add_u64 v[202:203], v[190:191], 0, v[160:161]
	v_add_co_u32_e32 v226, vcc, 0x80000, v186
	s_nop 1
	v_addc_co_u32_e32 v227, vcc, 0, v187, vcc
	global_load_dword v228, v[226:227], off
	global_load_dword v228, v[226:227], off offset:512
	v_add_co_u32_e32 v226, vcc, 0xc0000, v186
	s_nop 1
	v_addc_co_u32_e32 v227, vcc, 0, v187, vcc
	global_load_dword v228, v[226:227], off
	global_load_dword v228, v[226:227], off offset:512
	v_add_co_u32_e32 v226, vcc, 0x200000, v186
	s_nop 1
	v_addc_co_u32_e32 v227, vcc, 0, v187, vcc
	global_load_dword v228, v[226:227], off
	global_load_dword v228, v[226:227], off offset:512
	v_add_co_u32_e32 v226, vcc, 0x240000, v186
	s_nop 1
	v_addc_co_u32_e32 v227, vcc, 0, v187, vcc
	global_load_dword v228, v[226:227], off
	global_load_dword v228, v[226:227], off offset:512
	v_add_co_u32_e32 v226, vcc, 0x280000, v186
	s_nop 1
	v_addc_co_u32_e32 v227, vcc, 0, v187, vcc
	global_load_dword v228, v[226:227], off
	global_load_dword v228, v[226:227], off offset:512
	v_add_co_u32_e32 v226, vcc, 0x2c0000, v186
	s_nop 1
	v_addc_co_u32_e32 v227, vcc, 0, v187, vcc
	global_load_dword v228, v[226:227], off
	global_load_dword v228, v[226:227], off offset:512
	global_load_dwordx4 v[132:135], v[128:129], off
	s_nop 0
	global_load_dwordx4 v[128:131], v[136:137], off offset:528
	global_load_dwordx4 v[140:143], v[136:137], off offset:16
	s_nop 0
	global_load_dwordx4 v[136:139], v[136:137], off offset:512
	s_nop 0
	global_load_dwordx4 v[174:177], v[186:187], off offset:16
	global_load_dwordx4 v[178:181], v[186:187], off
	global_load_dwordx4 v[182:185], v[186:187], off offset:528
	s_nop 0
	global_load_dwordx4 v[186:189], v[186:187], off offset:512
	s_nop 0
	global_load_dwordx4 v[190:193], v[202:203], off
	global_load_dwordx4 v[194:197], v[202:203], off offset:16
	global_load_dwordx4 v[198:201], v[202:203], off offset:512
	s_nop 0
	global_load_dwordx4 v[202:205], v[202:203], off offset:528
	v_lshl_add_u64 v[164:165], v[164:165], 1, s[28:29]
	v_lshlrev_b64 v[210:211], 13, v[162:163]
	v_lshl_add_u64 v[164:165], v[164:165], 0, s[14:15]
	v_lshl_add_u64 v[210:211], v[164:165], 0, v[210:211]
	v_lshlrev_b64 v[206:207], 13, v[206:207]
	v_lshl_add_u64 v[206:207], v[164:165], 0, v[206:207]
	v_or_b32_e32 v208, 32, v162
	v_ashrrev_i32_e32 v209, 31, v208
	v_lshlrev_b64 v[212:213], 14, v[208:209]
	v_lshl_add_u64 v[212:213], s[26:27], 0, v[212:213]
	v_lshl_add_u64 v[212:213], v[212:213], 0, v[160:161]
	s_andn2_b64 vcc, exec, s[0:1]
	s_mov_b64 s[0:1], -1
	s_waitcnt vmcnt(0)
	v_pk_fma_f32 v[118:119], v[118:119], v[134:135], v[192:193]
	v_pk_fma_f32 v[126:127], v[126:127], v[134:135], v[180:181]
	v_pk_fma_f32 v[124:125], v[124:125], v[132:133], v[178:179]
	v_pk_fma_f32 v[122:123], v[122:123], v[142:143], v[176:177]
	v_pk_fma_f32 v[120:121], v[120:121], v[140:141], v[174:175]
	v_pk_fma_f32 v[174:175], v[98:99], v[130:131], v[204:205]
	v_pk_fma_f32 v[176:177], v[96:97], v[128:129], v[202:203]
	v_cvt_pk_bf16_f32 v96, v124, v125
	v_cvt_pk_bf16_f32 v97, v126, v127
	v_cvt_pk_bf16_f32 v98, v120, v121
	v_cvt_pk_bf16_f32 v99, v122, v123
	v_pk_fma_f32 v[110:111], v[110:111], v[138:139], v[188:189]
	v_pk_fma_f32 v[108:109], v[108:109], v[136:137], v[186:187]
	v_pk_fma_f32 v[106:107], v[106:107], v[130:131], v[184:185]
	v_pk_fma_f32 v[104:105], v[104:105], v[128:129], v[182:183]
	global_store_dwordx4 v[210:211], v[96:99], off
	v_pk_fma_f32 v[116:117], v[116:117], v[132:133], v[190:191]
	v_pk_fma_f32 v[114:115], v[114:115], v[142:143], v[196:197]
	v_cvt_pk_bf16_f32 v96, v108, v109
	v_cvt_pk_bf16_f32 v97, v110, v111
	v_cvt_pk_bf16_f32 v98, v104, v105
	v_cvt_pk_bf16_f32 v99, v106, v107
	v_pk_fma_f32 v[112:113], v[112:113], v[140:141], v[194:195]
	global_store_dwordx4 v[210:211], v[96:99], off offset:256
	v_pk_fma_f32 v[102:103], v[102:103], v[138:139], v[200:201]
	v_pk_fma_f32 v[100:101], v[100:101], v[136:137], v[198:199]
	v_cvt_pk_bf16_f32 v96, v116, v117
	v_cvt_pk_bf16_f32 v97, v118, v119
	v_cvt_pk_bf16_f32 v98, v112, v113
	v_cvt_pk_bf16_f32 v99, v114, v115
	global_store_dwordx4 v[206:207], v[96:99], off
	v_lshlrev_b64 v[178:179], 13, v[208:209]
	v_lshl_add_u64 v[178:179], v[164:165], 0, v[178:179]
	v_cvt_pk_bf16_f32 v96, v100, v101
	v_cvt_pk_bf16_f32 v97, v102, v103
	v_cvt_pk_bf16_f32 v98, v176, v177
	v_cvt_pk_bf16_f32 v99, v174, v175
	v_or_b32_e32 v174, 48, v162
	v_ashrrev_i32_e32 v175, 31, v174
	v_lshlrev_b64 v[112:113], 14, v[174:175]
	v_lshl_add_u64 v[112:113], s[26:27], 0, v[112:113]
	global_store_dwordx4 v[206:207], v[96:99], off offset:256
	v_lshl_add_u64 v[124:125], v[112:113], 0, v[160:161]
	global_load_dwordx4 v[96:99], v[212:213], off offset:16
	global_load_dwordx4 v[100:103], v[212:213], off
	global_load_dwordx4 v[104:107], v[212:213], off offset:528
	global_load_dwordx4 v[108:111], v[212:213], off offset:512
	global_load_dwordx4 v[112:115], v[124:125], off
	global_load_dwordx4 v[116:119], v[124:125], off offset:16
	global_load_dwordx4 v[120:123], v[124:125], off offset:512
	s_nop 0
	global_load_dwordx4 v[124:127], v[124:125], off offset:528
	v_lshlrev_b64 v[174:175], 13, v[174:175]
	v_lshl_add_u64 v[174:175], v[164:165], 0, v[174:175]
	v_add_u32_e32 v176, 0x80, v162
	v_ashrrev_i32_e32 v177, 31, v176
	v_lshlrev_b64 v[180:181], 14, v[176:177]
	v_lshl_add_u64 v[180:181], s[26:27], 0, v[180:181]
	v_lshl_add_u64 v[180:181], v[180:181], 0, v[160:161]
	s_waitcnt vmcnt(7)
;     template <class T> __device__ __forceinline__ T* w(size_t off) const { return (T*)(pp->ws + off); }
; __device__ __forceinline__ unsigned pk2(float lo, float hi) { return pg8::cvt_pk_bf16(lo, hi); }
;     __device__ __forceinline__ void operator()(const pg8::f32x4 (&acc)[2][2][4][2], const pg8::Unit& u, int wr, int wc, int fr, int fq) const {
;     ...
; #pragma unroll
;         for (int ai = 0; ai < 2; ++ai)
; #pragma unroll
;             for (int mp = 0; mp < 2; ++mp) {
;                 f32x4 xv[2][4];
; #pragma unroll
;                 for (int k = 0; k < 2; ++k) {
;                     const int m = mp * 2 + k;
;                     const int r = u.pm * 256 + ai * 128 + wr * 64 + m * 16 + fr;
; #pragma unroll
;                     for (int bj = 0; bj < 2; ++bj) {
;                         const int cc = cb + bj * 128;
;                         if (l == 0) { const float* xo = xp + (size_t)r * DM + cc; xv[k][bj * 2] = *(const f32x4*)xo; xv[k][bj * 2 + 1] = *(const f32x4*)(xo + 4); }
;                         else { const u32x4 w = *(const u32x4*)(X + (size_t)r * DM + cc);
;                             xv[k][bj * 2] = (f32x4){__uint_as_float(w.x << 16), __uint_as_float(w.x & 0xFFFF0000u), __uint_as_float(w.y << 16), __uint_as_float(w.y & 0xFFFF0000u)};
;                             xv[k][bj * 2 + 1] = (f32x4){__uint_as_float(w.z << 16), __uint_as_float(w.z & 0xFFFF0000u), __uint_as_float(w.w << 16), __uint_as_float(w.w & 0xFFFF0000u)}; }
;                     }
;                 }
; #pragma unroll
;                 for (int k = 0; k < 2; ++k) {
;                     const int m = mp * 2 + k;
;                     const int r = u.pm * 256 + ai * 128 + wr * 64 + m * 16 + fr;
; #pragma unroll
;                     for (int bj = 0; bj < 2; ++bj) {
;                         const f32x4 o0 = xv[k][bj * 2] + gv[bj * 2] * acc[ai][bj][m][0], o1 = xv[k][bj * 2 + 1] + gv[bj * 2 + 1] * acc[ai][bj][m][1];
;                         *(u32x4*)(X + (size_t)r * DM + cb + bj * 128) = (u32x4){pk2(o0[0], o0[1]), pk2(o0[2], o0[3]), pk2(o1[0], o1[1]), pk2(o1[2], o1[3])};
;                     }
;                 }
	v_pk_fma_f32 v[90:91], v[90:91], v[142:143], v[98:99]
	s_waitcnt vmcnt(6)
	v_pk_fma_f32 v[94:95], v[94:95], v[134:135], v[102:103]
	v_pk_fma_f32 v[92:93], v[92:93], v[132:133], v[100:101]
	v_pk_fma_f32 v[88:89], v[88:89], v[140:141], v[96:97]
	s_waitcnt vmcnt(0)
	v_pk_fma_f32 v[96:97], v[66:67], v[130:131], v[126:127]
	v_pk_fma_f32 v[98:99], v[64:65], v[128:129], v[124:125]
	v_cvt_pk_bf16_f32 v64, v92, v93
	v_cvt_pk_bf16_f32 v65, v94, v95
	v_cvt_pk_bf16_f32 v66, v88, v89
	v_cvt_pk_bf16_f32 v67, v90, v91
	v_pk_fma_f32 v[78:79], v[78:79], v[138:139], v[110:111]
	v_pk_fma_f32 v[76:77], v[76:77], v[136:137], v[108:109]
	v_pk_fma_f32 v[74:75], v[74:75], v[130:131], v[106:107]
	v_pk_fma_f32 v[72:73], v[72:73], v[128:129], v[104:105]
	global_store_dwordx4 v[178:179], v[64:67], off
	v_pk_fma_f32 v[86:87], v[86:87], v[134:135], v[114:115]
	v_pk_fma_f32 v[84:85], v[84:85], v[132:133], v[112:113]
	v_cvt_pk_bf16_f32 v64, v76, v77
	v_cvt_pk_bf16_f32 v65, v78, v79
	v_cvt_pk_bf16_f32 v66, v72, v73
	v_cvt_pk_bf16_f32 v67, v74, v75
	v_pk_fma_f32 v[82:83], v[82:83], v[142:143], v[118:119]
	v_pk_fma_f32 v[80:81], v[80:81], v[140:141], v[116:117]
	global_store_dwordx4 v[178:179], v[64:67], off offset:256
	v_pk_fma_f32 v[70:71], v[70:71], v[138:139], v[122:123]
	v_pk_fma_f32 v[68:69], v[68:69], v[136:137], v[120:121]
	v_cvt_pk_bf16_f32 v64, v84, v85
	v_cvt_pk_bf16_f32 v65, v86, v87
	v_cvt_pk_bf16_f32 v66, v80, v81
	v_cvt_pk_bf16_f32 v67, v82, v83
	global_store_dwordx4 v[174:175], v[64:67], off
	v_lshlrev_b64 v[100:101], 13, v[176:177]
	v_lshl_add_u64 v[100:101], v[164:165], 0, v[100:101]
	v_cvt_pk_bf16_f32 v64, v68, v69
	v_cvt_pk_bf16_f32 v65, v70, v71
	v_cvt_pk_bf16_f32 v66, v98, v99
	v_cvt_pk_bf16_f32 v67, v96, v97
	v_add_u32_e32 v96, 0x90, v162
	v_ashrrev_i32_e32 v97, 31, v96
	v_lshlrev_b64 v[80:81], 14, v[96:97]
	v_lshl_add_u64 v[80:81], s[26:27], 0, v[80:81]
	global_store_dwordx4 v[174:175], v[64:67], off offset:256
	v_lshl_add_u64 v[92:93], v[80:81], 0, v[160:161]
	global_load_dwordx4 v[64:67], v[180:181], off offset:16
	global_load_dwordx4 v[68:71], v[180:181], off
	global_load_dwordx4 v[72:75], v[180:181], off offset:528
	global_load_dwordx4 v[76:79], v[180:181], off offset:512
	global_load_dwordx4 v[80:83], v[92:93], off
	global_load_dwordx4 v[84:87], v[92:93], off offset:16
	global_load_dwordx4 v[88:91], v[92:93], off offset:512
	s_nop 0
	global_load_dwordx4 v[92:95], v[92:93], off offset:528
	v_lshlrev_b64 v[96:97], 13, v[96:97]
	v_lshl_add_u64 v[96:97], v[164:165], 0, v[96:97]
	v_add_u32_e32 v98, 0xa0, v162
	v_ashrrev_i32_e32 v99, 31, v98
	v_lshlrev_b64 v[102:103], 14, v[98:99]
	v_lshl_add_u64 v[102:103], s[26:27], 0, v[102:103]
	v_lshl_add_u64 v[102:103], v[102:103], 0, v[160:161]
	s_waitcnt vmcnt(7)
	v_pk_fma_f32 v[58:59], v[58:59], v[142:143], v[66:67]
	s_waitcnt vmcnt(6)
	v_pk_fma_f32 v[62:63], v[62:63], v[134:135], v[70:71]
	v_pk_fma_f32 v[60:61], v[60:61], v[132:133], v[68:69]
	v_pk_fma_f32 v[56:57], v[56:57], v[140:141], v[64:65]
	s_waitcnt vmcnt(0)
	v_pk_fma_f32 v[64:65], v[34:35], v[130:131], v[94:95]
	v_pk_fma_f32 v[66:67], v[32:33], v[128:129], v[92:93]
	v_cvt_pk_bf16_f32 v32, v60, v61
	v_cvt_pk_bf16_f32 v33, v62, v63
	v_cvt_pk_bf16_f32 v34, v56, v57
	v_cvt_pk_bf16_f32 v35, v58, v59
	v_pk_fma_f32 v[46:47], v[46:47], v[138:139], v[78:79]
	v_pk_fma_f32 v[44:45], v[44:45], v[136:137], v[76:77]
	v_pk_fma_f32 v[42:43], v[42:43], v[130:131], v[74:75]
	v_pk_fma_f32 v[40:41], v[40:41], v[128:129], v[72:73]
	global_store_dwordx4 v[100:101], v[32:35], off
	v_pk_fma_f32 v[54:55], v[54:55], v[134:135], v[82:83]
	v_pk_fma_f32 v[52:53], v[52:53], v[132:133], v[80:81]
	v_cvt_pk_bf16_f32 v32, v44, v45
	v_cvt_pk_bf16_f32 v33, v46, v47
	v_cvt_pk_bf16_f32 v34, v40, v41
	v_cvt_pk_bf16_f32 v35, v42, v43
	v_pk_fma_f32 v[50:51], v[50:51], v[142:143], v[86:87]
	v_pk_fma_f32 v[48:49], v[48:49], v[140:141], v[84:85]
	global_store_dwordx4 v[100:101], v[32:35], off offset:256
	v_pk_fma_f32 v[38:39], v[38:39], v[138:139], v[90:91]
	v_pk_fma_f32 v[36:37], v[36:37], v[136:137], v[88:89]
	v_cvt_pk_bf16_f32 v32, v52, v53
	v_cvt_pk_bf16_f32 v33, v54, v55
	v_cvt_pk_bf16_f32 v34, v48, v49
	v_cvt_pk_bf16_f32 v35, v50, v51
	global_store_dwordx4 v[96:97], v[32:35], off
	s_nop 1
	v_cvt_pk_bf16_f32 v32, v36, v37
	v_cvt_pk_bf16_f32 v33, v38, v39
	v_cvt_pk_bf16_f32 v34, v66, v67
	v_cvt_pk_bf16_f32 v35, v64, v65
	v_add_u32_e32 v64, 0xb0, v162
	v_ashrrev_i32_e32 v65, 31, v64
	v_lshlrev_b64 v[48:49], 14, v[64:65]
	v_lshl_add_u64 v[48:49], s[26:27], 0, v[48:49]
	global_store_dwordx4 v[96:97], v[32:35], off offset:256
	v_lshl_add_u64 v[60:61], v[48:49], 0, v[160:161]
	global_load_dwordx4 v[32:35], v[102:103], off offset:16
	global_load_dwordx4 v[36:39], v[102:103], off
	global_load_dwordx4 v[40:43], v[102:103], off offset:528
	global_load_dwordx4 v[44:47], v[102:103], off offset:512
	global_load_dwordx4 v[48:51], v[60:61], off
	global_load_dwordx4 v[52:55], v[60:61], off offset:16
	global_load_dwordx4 v[56:59], v[60:61], off offset:512
	s_nop 0
	global_load_dwordx4 v[60:63], v[60:61], off offset:528
	v_lshlrev_b64 v[66:67], 13, v[98:99]
	v_lshl_add_u64 v[66:67], v[164:165], 0, v[66:67]
	v_lshlrev_b64 v[64:65], 13, v[64:65]
	v_lshl_add_u64 v[64:65], v[164:165], 0, v[64:65]
	s_waitcnt vmcnt(7)
	v_pk_fma_f32 v[26:27], v[26:27], v[142:143], v[34:35]
	s_waitcnt vmcnt(6)
	v_pk_fma_f32 v[30:31], v[30:31], v[134:135], v[38:39]
	v_pk_fma_f32 v[28:29], v[28:29], v[132:133], v[36:37]
	v_pk_fma_f32 v[24:25], v[24:25], v[140:141], v[32:33]
	s_waitcnt vmcnt(0)
	v_pk_fma_f32 v[32:33], v[2:3], v[130:131], v[62:63]
	v_pk_fma_f32 v[34:35], v[0:1], v[128:129], v[60:61]
	v_cvt_pk_bf16_f32 v0, v28, v29
	v_cvt_pk_bf16_f32 v1, v30, v31
	v_cvt_pk_bf16_f32 v2, v24, v25
	v_cvt_pk_bf16_f32 v3, v26, v27
	v_pk_fma_f32 v[14:15], v[14:15], v[138:139], v[46:47]
	v_pk_fma_f32 v[12:13], v[12:13], v[136:137], v[44:45]
	v_pk_fma_f32 v[10:11], v[10:11], v[130:131], v[42:43]
	v_pk_fma_f32 v[8:9], v[8:9], v[128:129], v[40:41]
	global_store_dwordx4 v[66:67], v[0:3], off
	v_pk_fma_f32 v[22:23], v[22:23], v[134:135], v[50:51]
	v_pk_fma_f32 v[20:21], v[20:21], v[132:133], v[48:49]
	v_cvt_pk_bf16_f32 v0, v12, v13
	v_cvt_pk_bf16_f32 v1, v14, v15
	v_cvt_pk_bf16_f32 v2, v8, v9
	v_cvt_pk_bf16_f32 v3, v10, v11
	v_pk_fma_f32 v[18:19], v[18:19], v[142:143], v[54:55]
	v_pk_fma_f32 v[16:17], v[16:17], v[140:141], v[52:53]
	global_store_dwordx4 v[66:67], v[0:3], off offset:256
	v_pk_fma_f32 v[6:7], v[6:7], v[138:139], v[58:59]
	v_pk_fma_f32 v[4:5], v[4:5], v[136:137], v[56:57]
	v_cvt_pk_bf16_f32 v0, v20, v21
	v_cvt_pk_bf16_f32 v1, v22, v23
	v_cvt_pk_bf16_f32 v2, v16, v17
	v_cvt_pk_bf16_f32 v3, v18, v19
	global_store_dwordx4 v[64:65], v[0:3], off
	s_nop 1
	v_cvt_pk_bf16_f32 v0, v4, v5
	v_cvt_pk_bf16_f32 v1, v6, v7
	v_cvt_pk_bf16_f32 v2, v34, v35
	v_cvt_pk_bf16_f32 v3, v32, v33
	global_store_dwordx4 v[64:65], v[0:3], off offset:256
	s_cbranch_vccnz .LBB0_1605
	s_andn2_b64 vcc, exec, s[6:7]
	s_cbranch_vccnz .LBB0_1604
	s_barrier
	s_branch .LBB0_1604

;     __device__ __forceinline__ void operator()(const pg8::f32x4 (&acc)[2][2][4][2], const pg8::Unit& u, int wr, int wc, int fr, int fq) const {
;     ...
;         const float* const xp = q->in[I_XP];
;         const float* const MOD = (const float*)(q->ws + WS_MOD); bf16* const X = (bf16*)(q->ws + WS_X);
;         const int cb = u.pn * 256 + wc * 32 + 8 * fq;
;         f32x4 gv[4];
;         { const float* gate = MOD + (size_t)(l * 12 + modrow(u.pm * 256)) * 12288 + 8192 + cb;
;           gv[0] = *(const f32x4*)gate; gv[1] = *(const f32x4*)(gate + 4); gv[2] = *(const f32x4*)(gate + 128); gv[3] = *(const f32x4*)(gate + 132); }
; #pragma unroll
;         for (int ai = 0; ai < 2; ++ai)
; #pragma unroll
;             for (int mp = 0; mp < 2; ++mp) {
;                 f32x4 xv[2][4];
; #pragma unroll
;                 for (int k = 0; k < 2; ++k) {
;                     const int m = mp * 2 + k;
;                     const int r = u.pm * 256 + ai * 128 + wr * 64 + m * 16 + fr;
; #pragma unroll
;                     for (int bj = 0; bj < 2; ++bj) {
;                         const int cc = cb + bj * 128;
;                         if (l == 0) { const float* xo = xp + (size_t)r * DM + cc; xv[k][bj * 2] = *(const f32x4*)xo; xv[k][bj * 2 + 1] = *(const f32x4*)(xo + 4); }
;                         else { const u32x4 w = *(const u32x4*)(X + (size_t)r * DM + cc);
;                             xv[k][bj * 2] = (f32x4){__uint_as_float(w.x << 16), __uint_as_float(w.x & 0xFFFF0000u), __uint_as_float(w.y << 16), __uint_as_float(w.y & 0xFFFF0000u)};
;                             xv[k][bj * 2 + 1] = (f32x4){__uint_as_float(w.z << 16), __uint_as_float(w.z & 0xFFFF0000u), __uint_as_float(w.w << 16), __uint_as_float(w.w & 0xFFFF0000u)}; }
;                     }
;                 }
; #pragma unroll
;                 for (int k = 0; k < 2; ++k) {
;                     const int m = mp * 2 + k;
;                     const int r = u.pm * 256 + ai * 128 + wr * 64 + m * 16 + fr;
; #pragma unroll
;                     for (int bj = 0; bj < 2; ++bj) {
;                         const f32x4 o0 = xv[k][bj * 2] + gv[bj * 2] * acc[ai][bj][m][0], o1 = xv[k][bj * 2 + 1] + gv[bj * 2 + 1] * acc[ai][bj][m][1];
;                         *(u32x4*)(X + (size_t)r * DM + cb + bj * 128) = (u32x4){pk2(o0[0], o0[1]), pk2(o0[2], o0[3]), pk2(o1[0], o1[1]), pk2(o1[2], o1[3])};
;                     }
.LBB0_3066:
	s_mov_b64 s[24:25], s[90:91]
	s_load_dwordx2 s[26:27], s[24:25], 0xc0
	v_lshl_or_b32 v128, s48, 8, v170
	v_ashrrev_i32_e32 v129, 31, v128
	v_lshlrev_b64 v[162:163], 1, v[128:129]
	s_waitcnt lgkmcnt(0)
	s_add_u32 s24, s26, 0x1b400000
	s_addc_u32 s25, s27, 0
	s_lshl_b32 s15, s22, 8
	v_add_u32_e32 v164, s15, v168
	s_addk_i32 s15, 0xe000
	v_ashrrev_i32_e32 v165, 31, v164
	s_lshr_b32 s15, s15, 2
	v_lshlrev_b64 v[190:191], 13, v[164:165]
	s_ashr_i32 s17, s22, 3
	s_or_b32 s15, s15, 4
	v_lshl_add_u64 v[130:131], s[24:25], 0, v[190:191]
	s_cmp_lt_i32 s22, 32
	v_lshl_add_u64 v[130:131], v[130:131], 0, v[162:163]
	s_cselect_b32 s15, s17, s15
	global_load_dwordx4 v[174:177], v[130:131], off
	global_load_dwordx4 v[178:181], v[130:131], off offset:256
	v_add_co_u32_e32 v226, vcc, 0x40000, v130
	s_nop 1
	v_addc_co_u32_e32 v227, vcc, 0, v131, vcc
	global_load_dword v228, v[226:227], off
	global_load_dword v228, v[226:227], off offset:256
	v_add_co_u32_e32 v226, vcc, 0x60000, v130
	s_nop 1
	v_addc_co_u32_e32 v227, vcc, 0, v131, vcc
	global_load_dword v228, v[226:227], off
	global_load_dword v228, v[226:227], off offset:256
	v_add_co_u32_e32 v226, vcc, 0x100000, v130
	s_nop 1
	v_addc_co_u32_e32 v227, vcc, 0, v131, vcc
	global_load_dword v228, v[226:227], off
	global_load_dword v228, v[226:227], off offset:256
	v_add_co_u32_e32 v226, vcc, 0x120000, v130
	s_nop 1
	v_addc_co_u32_e32 v227, vcc, 0, v131, vcc
	global_load_dword v228, v[226:227], off
	global_load_dword v228, v[226:227], off offset:256
	v_add_co_u32_e32 v226, vcc, 0x140000, v130
	s_nop 1
	v_addc_co_u32_e32 v227, vcc, 0, v131, vcc
	global_load_dword v228, v[226:227], off
	global_load_dword v228, v[226:227], off offset:256
	v_add_co_u32_e32 v226, vcc, 0x160000, v130
	s_nop 1
	v_addc_co_u32_e32 v227, vcc, 0, v131, vcc
	global_load_dword v228, v[226:227], off
	global_load_dword v228, v[226:227], off offset:256
	v_or_b32_e32 v130, 16, v164
	s_add_i32 s15, s15, 12
	v_ashrrev_i32_e32 v131, 31, v130
	s_mul_hi_i32 s17, s15, 0xc000
	s_mul_i32 s15, s15, 0xc000
	v_lshlrev_b64 v[192:193], 13, v[130:131]
	s_add_u32 s26, s26, s15
	v_lshl_add_u64 v[130:131], s[24:25], 0, v[192:193]
	s_addc_u32 s27, s27, s17
	v_lshl_add_u64 v[130:131], v[130:131], 0, v[162:163]
	v_lshl_add_u64 v[128:129], v[128:129], 2, s[26:27]
	global_load_dwordx4 v[182:185], v[130:131], off
	global_load_dwordx4 v[186:189], v[130:131], off offset:256
	v_add_co_u32_e32 v130, vcc, s47, v128
	v_lshl_add_u64 v[160:161], s[24:25], 0, v[162:163]
	s_nop 0
	v_addc_co_u32_e32 v131, vcc, 0, v129, vcc
	v_lshl_add_u64 v[128:129], v[128:129], 0, s[12:13]
	global_load_dwordx4 v[140:143], v[130:131], off
	global_load_dwordx4 v[136:139], v[128:129], off offset:16
	global_load_dwordx4 v[132:135], v[128:129], off offset:512
	s_nop 0
	global_load_dwordx4 v[128:131], v[128:129], off offset:528
	v_lshl_add_u64 v[190:191], v[160:161], 0, v[190:191]
	v_lshl_add_u64 v[192:193], v[160:161], 0, v[192:193]
	s_andn2_b64 vcc, exec, s[0:1]
	s_mov_b64 s[0:1], -1
	s_waitcnt vmcnt(0)
	v_lshlrev_b32_e32 v194, 16, v174
	v_and_b32_e32 v195, 0xffff0000, v174
	v_lshlrev_b32_e32 v174, 16, v175
	v_and_b32_e32 v175, 0xffff0000, v175
	v_lshlrev_b32_e32 v196, 16, v176
	v_and_b32_e32 v197, 0xffff0000, v176
	v_lshlrev_b32_e32 v176, 16, v177
	v_and_b32_e32 v177, 0xffff0000, v177
	v_lshlrev_b32_e32 v200, 16, v180
	v_and_b32_e32 v201, 0xffff0000, v180
	v_lshlrev_b32_e32 v198, 16, v178
	v_and_b32_e32 v199, 0xffff0000, v178
	v_lshlrev_b32_e32 v178, 16, v179
	v_and_b32_e32 v179, 0xffff0000, v179
	v_lshlrev_b32_e32 v180, 16, v181
	v_and_b32_e32 v181, 0xffff0000, v181
	v_lshlrev_b32_e32 v202, 16, v182
	v_and_b32_e32 v203, 0xffff0000, v182
	v_lshlrev_b32_e32 v182, 16, v183
	v_and_b32_e32 v183, 0xffff0000, v183
	v_pk_fma_f32 v[122:123], v[122:123], v[138:139], v[176:177]
	v_pk_fma_f32 v[126:127], v[126:127], v[142:143], v[174:175]
	v_pk_fma_f32 v[124:125], v[124:125], v[140:141], v[194:195]
	v_pk_fma_f32 v[176:177], v[104:105], v[128:129], v[200:201]
	v_cvt_pk_bf16_f32 v104, v124, v125
	v_cvt_pk_bf16_f32 v105, v126, v127
	v_lshlrev_b32_e32 v206, 16, v186
	v_and_b32_e32 v207, 0xffff0000, v186
	v_pk_fma_f32 v[120:121], v[120:121], v[136:137], v[196:197]
	v_pk_fma_f32 v[110:111], v[110:111], v[134:135], v[178:179]
	v_pk_fma_f32 v[108:109], v[108:109], v[132:133], v[198:199]
	v_pk_fma_f32 v[174:175], v[106:107], v[130:131], v[180:181]
	v_cvt_pk_bf16_f32 v106, v120, v121
	v_cvt_pk_bf16_f32 v107, v122, v123
	global_store_dwordx4 v[190:191], v[104:107], off
	v_lshlrev_b32_e32 v204, 16, v184
	v_and_b32_e32 v205, 0xffff0000, v184
	v_cvt_pk_bf16_f32 v104, v108, v109
	v_cvt_pk_bf16_f32 v105, v110, v111
	v_lshlrev_b32_e32 v184, 16, v185
	v_and_b32_e32 v185, 0xffff0000, v185
	v_lshlrev_b32_e32 v208, 16, v188
	v_and_b32_e32 v209, 0xffff0000, v188
	v_lshlrev_b32_e32 v188, 16, v189
	v_and_b32_e32 v189, 0xffff0000, v189
	v_pk_fma_f32 v[118:119], v[118:119], v[142:143], v[182:183]
	v_pk_fma_f32 v[116:117], v[116:117], v[140:141], v[202:203]
	v_cvt_pk_bf16_f32 v106, v176, v177
	v_cvt_pk_bf16_f32 v107, v174, v175
	global_store_dwordx4 v[190:191], v[104:107], off offset:256
	v_pk_fma_f32 v[100:101], v[100:101], v[132:133], v[206:207]
	v_pk_fma_f32 v[114:115], v[114:115], v[138:139], v[184:185]
	v_cvt_pk_bf16_f32 v104, v116, v117
	v_cvt_pk_bf16_f32 v105, v118, v119
	v_pk_fma_f32 v[112:113], v[112:113], v[136:137], v[204:205]
	v_or_b32_e32 v108, 48, v164
	v_cvt_pk_bf16_f32 v106, v112, v113
	v_cvt_pk_bf16_f32 v107, v114, v115
	global_store_dwordx4 v[192:193], v[104:107], off
	v_lshlrev_b32_e32 v186, 16, v187
	v_and_b32_e32 v187, 0xffff0000, v187
	v_pk_fma_f32 v[104:105], v[98:99], v[130:131], v[188:189]
	v_pk_fma_f32 v[98:99], v[96:97], v[128:129], v[208:209]
	v_cvt_pk_bf16_f32 v96, v100, v101
	v_or_b32_e32 v100, 32, v164
	v_ashrrev_i32_e32 v101, 31, v100
	v_lshlrev_b64 v[116:117], 13, v[100:101]
	v_lshl_add_u64 v[100:101], s[24:25], 0, v[116:117]
	v_ashrrev_i32_e32 v109, 31, v108
	v_pk_fma_f32 v[102:103], v[102:103], v[134:135], v[186:187]
	v_lshlrev_b64 v[118:119], 13, v[108:109]
	v_cvt_pk_bf16_f32 v97, v102, v103
	v_cvt_pk_bf16_f32 v98, v98, v99
	v_cvt_pk_bf16_f32 v99, v104, v105
	v_lshl_add_u64 v[104:105], v[100:101], 0, v[162:163]
	global_load_dwordx4 v[100:103], v[104:105], off
	s_nop 0
	global_load_dwordx4 v[104:107], v[104:105], off offset:256
	v_lshl_add_u64 v[108:109], s[24:25], 0, v[118:119]
	v_lshl_add_u64 v[112:113], v[108:109], 0, v[162:163]
	global_load_dwordx4 v[108:111], v[112:113], off
	s_nop 0
	global_load_dwordx4 v[112:115], v[112:113], off offset:256
	v_lshl_add_u64 v[116:117], v[160:161], 0, v[116:117]
	global_store_dwordx4 v[192:193], v[96:99], off offset:256
	v_lshl_add_u64 v[118:119], v[160:161], 0, v[118:119]
	s_waitcnt vmcnt(3)
;     template <class T> __device__ __forceinline__ T* w(size_t off) const { return (T*)(pp->ws + off); }
; __device__ __forceinline__ unsigned pk2(float lo, float hi) { return pg8::cvt_pk_bf16(lo, hi); }
;     __device__ __forceinline__ void operator()(const pg8::f32x4 (&acc)[2][2][4][2], const pg8::Unit& u, int wr, int wc, int fr, int fq) const {
;     ...
; #pragma unroll
;         for (int ai = 0; ai < 2; ++ai)
; #pragma unroll
;             for (int mp = 0; mp < 2; ++mp) {
;                 f32x4 xv[2][4];
; #pragma unroll
;                 for (int k = 0; k < 2; ++k) {
;                     const int m = mp * 2 + k;
;                     const int r = u.pm * 256 + ai * 128 + wr * 64 + m * 16 + fr;
; #pragma unroll
;                     for (int bj = 0; bj < 2; ++bj) {
;                         const int cc = cb + bj * 128;
;                         if (l == 0) { const float* xo = xp + (size_t)r * DM + cc; xv[k][bj * 2] = *(const f32x4*)xo; xv[k][bj * 2 + 1] = *(const f32x4*)(xo + 4); }
;                         else { const u32x4 w = *(const u32x4*)(X + (size_t)r * DM + cc);
;                             xv[k][bj * 2] = (f32x4){__uint_as_float(w.x << 16), __uint_as_float(w.x & 0xFFFF0000u), __uint_as_float(w.y << 16), __uint_as_float(w.y & 0xFFFF0000u)};
;                             xv[k][bj * 2 + 1] = (f32x4){__uint_as_float(w.z << 16), __uint_as_float(w.z & 0xFFFF0000u), __uint_as_float(w.w << 16), __uint_as_float(w.w & 0xFFFF0000u)}; }
;                     }
;                 }
; #pragma unroll
;                 for (int k = 0; k < 2; ++k) {
;                     const int m = mp * 2 + k;
;                     const int r = u.pm * 256 + ai * 128 + wr * 64 + m * 16 + fr;
; #pragma unroll
;                     for (int bj = 0; bj < 2; ++bj) {
;                         const f32x4 o0 = xv[k][bj * 2] + gv[bj * 2] * acc[ai][bj][m][0], o1 = xv[k][bj * 2 + 1] + gv[bj * 2 + 1] * acc[ai][bj][m][1];
;                         *(u32x4*)(X + (size_t)r * DM + cb + bj * 128) = (u32x4){pk2(o0[0], o0[1]), pk2(o0[2], o0[3]), pk2(o1[0], o1[1]), pk2(o1[2], o1[3])};
;                     }
;                 }
	v_lshlrev_b32_e32 v122, 16, v106
	v_lshlrev_b32_e32 v96, 16, v100
	v_and_b32_e32 v97, 0xffff0000, v100
	v_lshlrev_b32_e32 v98, 16, v101
	v_and_b32_e32 v99, 0xffff0000, v101
	v_and_b32_e32 v123, 0xffff0000, v106
	v_lshlrev_b32_e32 v100, 16, v102
	v_and_b32_e32 v101, 0xffff0000, v102
	v_lshlrev_b32_e32 v102, 16, v103
	v_and_b32_e32 v103, 0xffff0000, v103
	v_lshlrev_b32_e32 v120, 16, v104
	v_and_b32_e32 v121, 0xffff0000, v104
	v_lshlrev_b32_e32 v104, 16, v105
	v_and_b32_e32 v105, 0xffff0000, v105
	v_lshlrev_b32_e32 v106, 16, v107
	v_and_b32_e32 v107, 0xffff0000, v107
	v_pk_fma_f32 v[94:95], v[94:95], v[142:143], v[98:99]
	v_pk_fma_f32 v[92:93], v[92:93], v[140:141], v[96:97]
	v_pk_fma_f32 v[98:99], v[72:73], v[128:129], v[122:123]
	v_cvt_pk_bf16_f32 v72, v92, v93
	v_cvt_pk_bf16_f32 v73, v94, v95
	s_waitcnt vmcnt(2)
	v_lshlrev_b32_e32 v124, 16, v108
	v_and_b32_e32 v125, 0xffff0000, v108
	v_lshlrev_b32_e32 v108, 16, v109
	v_and_b32_e32 v109, 0xffff0000, v109
	s_waitcnt vmcnt(1)
	v_lshlrev_b32_e32 v174, 16, v112
	v_and_b32_e32 v175, 0xffff0000, v112
	v_pk_fma_f32 v[90:91], v[90:91], v[138:139], v[102:103]
	v_pk_fma_f32 v[88:89], v[88:89], v[136:137], v[100:101]
	v_pk_fma_f32 v[78:79], v[78:79], v[134:135], v[104:105]
	v_pk_fma_f32 v[76:77], v[76:77], v[132:133], v[120:121]
	v_pk_fma_f32 v[96:97], v[74:75], v[130:131], v[106:107]
	v_cvt_pk_bf16_f32 v74, v88, v89
	v_cvt_pk_bf16_f32 v75, v90, v91
	global_store_dwordx4 v[116:117], v[72:75], off
	v_lshlrev_b32_e32 v126, 16, v110
	v_and_b32_e32 v127, 0xffff0000, v110
	v_cvt_pk_bf16_f32 v72, v76, v77
	v_cvt_pk_bf16_f32 v73, v78, v79
	v_lshlrev_b32_e32 v110, 16, v111
	v_and_b32_e32 v111, 0xffff0000, v111
	v_lshlrev_b32_e32 v176, 16, v114
	v_and_b32_e32 v177, 0xffff0000, v114
	v_lshlrev_b32_e32 v114, 16, v115
	v_and_b32_e32 v115, 0xffff0000, v115
	v_pk_fma_f32 v[86:87], v[86:87], v[142:143], v[108:109]
	v_pk_fma_f32 v[84:85], v[84:85], v[140:141], v[124:125]
	v_cvt_pk_bf16_f32 v74, v98, v99
	v_cvt_pk_bf16_f32 v75, v96, v97
	global_store_dwordx4 v[116:117], v[72:75], off offset:256
	v_pk_fma_f32 v[68:69], v[68:69], v[132:133], v[174:175]
	v_pk_fma_f32 v[82:83], v[82:83], v[138:139], v[110:111]
	v_cvt_pk_bf16_f32 v72, v84, v85
	v_cvt_pk_bf16_f32 v73, v86, v87
	v_pk_fma_f32 v[80:81], v[80:81], v[136:137], v[126:127]
	v_add_u32_e32 v76, 0x90, v164
	v_cvt_pk_bf16_f32 v74, v80, v81
	v_cvt_pk_bf16_f32 v75, v82, v83
	global_store_dwordx4 v[118:119], v[72:75], off
	v_ashrrev_i32_e32 v77, 31, v76
	v_lshlrev_b64 v[86:87], 13, v[76:77]
	v_pk_fma_f32 v[72:73], v[66:67], v[130:131], v[114:115]
	v_pk_fma_f32 v[66:67], v[64:65], v[128:129], v[176:177]
	v_cvt_pk_bf16_f32 v64, v68, v69
	v_add_u32_e32 v68, 0x80, v164
	v_ashrrev_i32_e32 v69, 31, v68
	v_lshlrev_b64 v[84:85], 13, v[68:69]
	v_lshlrev_b32_e32 v112, 16, v113
	v_and_b32_e32 v113, 0xffff0000, v113
	v_lshl_add_u64 v[68:69], s[24:25], 0, v[84:85]
	v_lshl_add_u64 v[76:77], s[24:25], 0, v[86:87]
	v_pk_fma_f32 v[70:71], v[70:71], v[134:135], v[112:113]
	v_lshl_add_u64 v[80:81], v[76:77], 0, v[162:163]
	v_cvt_pk_bf16_f32 v65, v70, v71
	v_cvt_pk_bf16_f32 v66, v66, v67
	v_cvt_pk_bf16_f32 v67, v72, v73
	v_lshl_add_u64 v[72:73], v[68:69], 0, v[162:163]
	global_load_dwordx4 v[68:71], v[72:73], off
	s_nop 0
	global_load_dwordx4 v[72:75], v[72:73], off offset:256
	s_nop 0
	global_load_dwordx4 v[76:79], v[80:81], off
	s_nop 0
	global_load_dwordx4 v[80:83], v[80:81], off offset:256
	v_lshl_add_u64 v[84:85], v[160:161], 0, v[84:85]
	global_store_dwordx4 v[118:119], v[64:67], off offset:256
	v_lshl_add_u64 v[86:87], v[160:161], 0, v[86:87]
	s_waitcnt vmcnt(3)
	v_lshlrev_b32_e32 v88, 16, v72
	v_lshlrev_b32_e32 v64, 16, v68
	v_and_b32_e32 v65, 0xffff0000, v68
	v_lshlrev_b32_e32 v66, 16, v69
	v_and_b32_e32 v67, 0xffff0000, v69
	s_waitcnt vmcnt(1)
;     template <class T> __device__ __forceinline__ T* w(size_t off) const { return (T*)(pp->ws + off); }
; __device__ __forceinline__ unsigned pk2(float lo, float hi) { return pg8::cvt_pk_bf16(lo, hi); }
;     __device__ __forceinline__ void operator()(const pg8::f32x4 (&acc)[2][2][4][2], const pg8::Unit& u, int wr, int wc, int fr, int fq) const {
;     ...
; #pragma unroll
;         for (int ai = 0; ai < 2; ++ai)
; #pragma unroll
;             for (int mp = 0; mp < 2; ++mp) {
;                 f32x4 xv[2][4];
; #pragma unroll
;                 for (int k = 0; k < 2; ++k) {
;                     const int m = mp * 2 + k;
;                     const int r = u.pm * 256 + ai * 128 + wr * 64 + m * 16 + fr;
; #pragma unroll
;                     for (int bj = 0; bj < 2; ++bj) {
;                         const int cc = cb + bj * 128;
;                         if (l == 0) { const float* xo = xp + (size_t)r * DM + cc; xv[k][bj * 2] = *(const f32x4*)xo; xv[k][bj * 2 + 1] = *(const f32x4*)(xo + 4); }
;                         else { const u32x4 w = *(const u32x4*)(X + (size_t)r * DM + cc);
;                             xv[k][bj * 2] = (f32x4){__uint_as_float(w.x << 16), __uint_as_float(w.x & 0xFFFF0000u), __uint_as_float(w.y << 16), __uint_as_float(w.y & 0xFFFF0000u)};
;                             xv[k][bj * 2 + 1] = (f32x4){__uint_as_float(w.z << 16), __uint_as_float(w.z & 0xFFFF0000u), __uint_as_float(w.w << 16), __uint_as_float(w.w & 0xFFFF0000u)}; }
;                     }
;                 }
; #pragma unroll
;                 for (int k = 0; k < 2; ++k) {
;                     const int m = mp * 2 + k;
;                     const int r = u.pm * 256 + ai * 128 + wr * 64 + m * 16 + fr;
; #pragma unroll
;                     for (int bj = 0; bj < 2; ++bj) {
;                         const f32x4 o0 = xv[k][bj * 2] + gv[bj * 2] * acc[ai][bj][m][0], o1 = xv[k][bj * 2 + 1] + gv[bj * 2 + 1] * acc[ai][bj][m][1];
;                         *(u32x4*)(X + (size_t)r * DM + cb + bj * 128) = (u32x4){pk2(o0[0], o0[1]), pk2(o0[2], o0[3]), pk2(o1[0], o1[1]), pk2(o1[2], o1[3])};
;                     }
;                 }
	v_lshlrev_b32_e32 v96, 16, v80
	v_and_b32_e32 v97, 0xffff0000, v80
	v_lshlrev_b32_e32 v80, 16, v81
	v_and_b32_e32 v81, 0xffff0000, v81
	v_lshlrev_b32_e32 v68, 16, v70
	v_and_b32_e32 v69, 0xffff0000, v70
	v_lshlrev_b32_e32 v70, 16, v71
	v_and_b32_e32 v71, 0xffff0000, v71
	v_and_b32_e32 v89, 0xffff0000, v72
	v_lshlrev_b32_e32 v72, 16, v73
	v_and_b32_e32 v73, 0xffff0000, v73
	v_lshlrev_b32_e32 v90, 16, v74
	v_and_b32_e32 v91, 0xffff0000, v74
	v_pk_fma_f32 v[62:63], v[62:63], v[142:143], v[66:67]
	v_pk_fma_f32 v[60:61], v[60:61], v[140:141], v[64:65]
	v_pk_fma_f32 v[66:67], v[38:39], v[134:135], v[80:81]
	v_cvt_pk_bf16_f32 v38, v60, v61
	v_cvt_pk_bf16_f32 v39, v62, v63
	v_lshlrev_b32_e32 v74, 16, v75
	v_and_b32_e32 v75, 0xffff0000, v75
	v_lshlrev_b32_e32 v92, 16, v76
	v_and_b32_e32 v93, 0xffff0000, v76
	v_lshlrev_b32_e32 v76, 16, v77
	v_and_b32_e32 v77, 0xffff0000, v77
	v_pk_fma_f32 v[58:59], v[58:59], v[138:139], v[70:71]
	v_pk_fma_f32 v[56:57], v[56:57], v[136:137], v[68:69]
	v_pk_fma_f32 v[46:47], v[46:47], v[134:135], v[72:73]
	v_pk_fma_f32 v[44:45], v[44:45], v[132:133], v[88:89]
	v_pk_fma_f32 v[64:65], v[40:41], v[128:129], v[90:91]
	v_cvt_pk_bf16_f32 v40, v56, v57
	v_cvt_pk_bf16_f32 v41, v58, v59
	global_store_dwordx4 v[84:85], v[38:41], off
	v_lshlrev_b32_e32 v94, 16, v78
	v_and_b32_e32 v95, 0xffff0000, v78
	v_cvt_pk_bf16_f32 v38, v44, v45
	v_cvt_pk_bf16_f32 v39, v46, v47
	v_lshlrev_b32_e32 v78, 16, v79
	v_and_b32_e32 v79, 0xffff0000, v79
	v_lshlrev_b32_e32 v98, 16, v82
	v_and_b32_e32 v99, 0xffff0000, v82
	v_lshlrev_b32_e32 v82, 16, v83
	v_and_b32_e32 v83, 0xffff0000, v83
	v_pk_fma_f32 v[42:43], v[42:43], v[130:131], v[74:75]
	v_pk_fma_f32 v[54:55], v[54:55], v[142:143], v[76:77]
	v_pk_fma_f32 v[52:53], v[52:53], v[140:141], v[92:93]
	v_cvt_pk_bf16_f32 v40, v64, v65
	v_cvt_pk_bf16_f32 v41, v42, v43
	global_store_dwordx4 v[84:85], v[38:41], off offset:256
	v_pk_fma_f32 v[36:37], v[36:37], v[132:133], v[96:97]
	v_pk_fma_f32 v[50:51], v[50:51], v[138:139], v[78:79]
	v_cvt_pk_bf16_f32 v38, v52, v53
	v_cvt_pk_bf16_f32 v39, v54, v55
	v_pk_fma_f32 v[48:49], v[48:49], v[136:137], v[94:95]
	v_add_u32_e32 v44, 0xb0, v164
	v_cvt_pk_bf16_f32 v40, v48, v49
	v_cvt_pk_bf16_f32 v41, v50, v51
	global_store_dwordx4 v[86:87], v[38:41], off
	v_ashrrev_i32_e32 v45, 31, v44
	v_lshlrev_b64 v[54:55], 13, v[44:45]
	v_pk_fma_f32 v[38:39], v[34:35], v[130:131], v[82:83]
	v_pk_fma_f32 v[34:35], v[32:33], v[128:129], v[98:99]
	v_cvt_pk_bf16_f32 v32, v36, v37
	v_add_u32_e32 v36, 0xa0, v164
	v_ashrrev_i32_e32 v37, 31, v36
	v_lshlrev_b64 v[52:53], 13, v[36:37]
	v_lshl_add_u64 v[36:37], s[24:25], 0, v[52:53]
	v_lshl_add_u64 v[44:45], s[24:25], 0, v[54:55]
	v_lshl_add_u64 v[40:41], v[36:37], 0, v[162:163]
	v_lshl_add_u64 v[48:49], v[44:45], 0, v[162:163]
	v_cvt_pk_bf16_f32 v33, v66, v67
	v_cvt_pk_bf16_f32 v34, v34, v35
	v_cvt_pk_bf16_f32 v35, v38, v39
	global_load_dwordx4 v[36:39], v[40:41], off
	s_nop 0
	global_load_dwordx4 v[40:43], v[40:41], off offset:256
	s_nop 0
	global_load_dwordx4 v[44:47], v[48:49], off
	s_nop 0
	global_load_dwordx4 v[48:51], v[48:49], off offset:256
	v_lshl_add_u64 v[52:53], v[160:161], 0, v[52:53]
	global_store_dwordx4 v[86:87], v[32:35], off offset:256
	v_lshl_add_u64 v[54:55], v[160:161], 0, v[54:55]
	s_waitcnt vmcnt(3)
	v_lshlrev_b32_e32 v56, 16, v40
	v_lshlrev_b32_e32 v32, 16, v36
	v_and_b32_e32 v33, 0xffff0000, v36
	v_lshlrev_b32_e32 v34, 16, v37
	v_and_b32_e32 v35, 0xffff0000, v37
	s_waitcnt vmcnt(1)
	v_lshlrev_b32_e32 v64, 16, v48
	v_and_b32_e32 v65, 0xffff0000, v48
	v_lshlrev_b32_e32 v36, 16, v38
	v_and_b32_e32 v37, 0xffff0000, v38
	v_lshlrev_b32_e32 v38, 16, v39
	v_and_b32_e32 v39, 0xffff0000, v39
	v_and_b32_e32 v57, 0xffff0000, v40
	v_lshlrev_b32_e32 v40, 16, v41
	v_and_b32_e32 v41, 0xffff0000, v41
	v_lshlrev_b32_e32 v48, 16, v49
	v_and_b32_e32 v49, 0xffff0000, v49
	v_pk_fma_f32 v[30:31], v[30:31], v[142:143], v[34:35]
	v_pk_fma_f32 v[28:29], v[28:29], v[140:141], v[32:33]
	v_pk_fma_f32 v[34:35], v[4:5], v[132:133], v[64:65]
	v_cvt_pk_bf16_f32 v4, v28, v29
	v_cvt_pk_bf16_f32 v5, v30, v31
	v_lshlrev_b32_e32 v58, 16, v42
	v_and_b32_e32 v59, 0xffff0000, v42
	v_lshlrev_b32_e32 v42, 16, v43
	v_and_b32_e32 v43, 0xffff0000, v43
	v_lshlrev_b32_e32 v60, 16, v44
	v_and_b32_e32 v61, 0xffff0000, v44
	v_lshlrev_b32_e32 v44, 16, v45
	v_and_b32_e32 v45, 0xffff0000, v45
	v_pk_fma_f32 v[26:27], v[26:27], v[138:139], v[38:39]
	v_pk_fma_f32 v[24:25], v[24:25], v[136:137], v[36:37]
	v_pk_fma_f32 v[14:15], v[14:15], v[134:135], v[40:41]
	v_pk_fma_f32 v[12:13], v[12:13], v[132:133], v[56:57]
	v_pk_fma_f32 v[32:33], v[6:7], v[134:135], v[48:49]
	v_cvt_pk_bf16_f32 v6, v24, v25
	v_cvt_pk_bf16_f32 v7, v26, v27
	global_store_dwordx4 v[52:53], v[4:7], off
	v_lshlrev_b32_e32 v62, 16, v46
	v_and_b32_e32 v63, 0xffff0000, v46
	v_cvt_pk_bf16_f32 v4, v12, v13
	v_cvt_pk_bf16_f32 v5, v14, v15
	v_lshlrev_b32_e32 v46, 16, v47
	v_and_b32_e32 v47, 0xffff0000, v47
	v_lshlrev_b32_e32 v66, 16, v50
	v_and_b32_e32 v67, 0xffff0000, v50
	v_lshlrev_b32_e32 v50, 16, v51
	v_and_b32_e32 v51, 0xffff0000, v51
	v_pk_fma_f32 v[10:11], v[10:11], v[130:131], v[42:43]
	v_pk_fma_f32 v[8:9], v[8:9], v[128:129], v[58:59]
	v_pk_fma_f32 v[22:23], v[22:23], v[142:143], v[44:45]
	v_pk_fma_f32 v[20:21], v[20:21], v[140:141], v[60:61]
	v_cvt_pk_bf16_f32 v6, v8, v9
	v_cvt_pk_bf16_f32 v7, v10, v11
	global_store_dwordx4 v[52:53], v[4:7], off offset:256
	v_pk_fma_f32 v[18:19], v[18:19], v[138:139], v[46:47]
	v_pk_fma_f32 v[16:17], v[16:17], v[136:137], v[62:63]
	v_cvt_pk_bf16_f32 v4, v20, v21
	v_cvt_pk_bf16_f32 v5, v22, v23
	s_nop 0
	v_cvt_pk_bf16_f32 v6, v16, v17
	v_cvt_pk_bf16_f32 v7, v18, v19
	global_store_dwordx4 v[54:55], v[4:7], off
	s_nop 1
	v_pk_fma_f32 v[4:5], v[2:3], v[130:131], v[50:51]
	v_pk_fma_f32 v[2:3], v[0:1], v[128:129], v[66:67]
	v_cvt_pk_bf16_f32 v0, v34, v35
	v_cvt_pk_bf16_f32 v1, v32, v33
	s_nop 0
	v_cvt_pk_bf16_f32 v2, v2, v3
	v_cvt_pk_bf16_f32 v3, v4, v5
	global_store_dwordx4 v[54:55], v[0:3], off offset:256
	s_cbranch_vccnz .LBB0_3055
	s_andn2_b64 vcc, exec, s[6:7]
	s_cbranch_vccnz .LBB0_3054
	s_barrier
	s_branch .LBB0_3054
